# P4: alternating-sum rows moved off the DFT workgroups (now on workgroups 128..255), its four serialized loads issued together, wave sum via DPP
# baseline (speedup 1.0000x reference)
; __device__ __forceinline__ int obid() { int b = (int)blockIdx.x; asm volatile("" : "+s"(b)); return b; }
; __device__ __forceinline__ int otid() { int t; asm volatile("v_mov_b32 %0, %1" : "=v"(t) : "v"(threadIdx.x)); return t; }
; __device__ __forceinline__ void ph_alt(const Params& p_) {
;     ...
;     const int tid = otid(), lane = tid & 63, wave = tid >> 6; const bf16* PQF = (const bf16*)(p.ws + WS_PQF);
;     float* dst = (float*)(p.ws + WS_PART) + (size_t)(2 * 2304 + 2 * 2048) * 512;
;     for (int r = obid() * 8 + wave; r < NB * DG; r += gridDim.x * 8) {
.LBB0_597:
	s_mov_b64 s[36:37], s[0:1]
	s_mov_b32 s3, s70
	s_movk_i32 s12, 0x80
	s_sub_i32 s3, s3, s12
	s_cmp_lt_i32 s3, 0
	s_cselect_b32 s3, s12, s3
	v_mov_b32 v0, v147
	s_nop 0
	v_ashrrev_i32_e32 v2, 6, v0
	v_lshl_add_u32 v2, s3, 3, v2
	s_movk_i32 s3, 0x400
	v_cmp_gt_i32_e32 vcc, s3, v2
	s_and_saveexec_b64 s[38:39], vcc
	v_readlane_b32 s24, v255, 36
	s_cbranch_execz .LBB0_602
	s_load_dwordx2 s[12:13], s[36:37], 0x90
	v_and_b32_e32 v3, 63, v0
	v_lshlrev_b32_e32 v0, 4, v3
	v_xor_b32_e32 v6, 2, v178
	v_xor_b32_e32 v7, 4, v178
	s_waitcnt lgkmcnt(0)
	v_lshl_add_u64 v[4:5], s[12:13], 0, v[0:1]
	v_and_b32_e32 v0, 64, v178
	v_add_u32_e32 v10, 64, v0
	v_xor_b32_e32 v0, 1, v178
	v_cmp_lt_i32_e32 vcc, v0, v10
	v_xor_b32_e32 v8, 8, v178
	v_xor_b32_e32 v9, 16, v178
	v_cndmask_b32_e32 v0, v178, v0, vcc
	v_cmp_lt_i32_e32 vcc, v6, v10
	v_xor_b32_e32 v11, 32, v178
	s_add_u32 s40, s12, 0x9e20000
	v_cndmask_b32_e32 v6, v178, v6, vcc
	v_cmp_lt_i32_e32 vcc, v7, v10
	s_addc_u32 s41, s13, 0
	s_mov_b64 s[12:13], 0x6400000
	v_cndmask_b32_e32 v7, v178, v7, vcc
	v_cmp_lt_i32_e32 vcc, v8, v10
	v_lshl_add_u64 v[4:5], v[4:5], 0, s[12:13]
	v_lshlrev_b32_e32 v0, 2, v0
	v_cndmask_b32_e32 v8, v178, v8, vcc
	v_cmp_lt_i32_e32 vcc, v9, v10
	v_lshlrev_b32_e32 v6, 2, v6
	v_lshlrev_b32_e32 v7, 2, v7
	v_cndmask_b32_e32 v9, v178, v9, vcc
	v_cmp_lt_i32_e32 vcc, v11, v10
	v_lshlrev_b32_e32 v8, 2, v8
	v_lshlrev_b32_e32 v9, 2, v9
	v_cndmask_b32_e32 v10, v178, v11, vcc
	v_lshlrev_b32_e32 v10, 2, v10
	v_cmp_eq_u32_e32 vcc, 0, v3
	s_mov_b64 s[42:43], 0
	s_branch .LBB0_600

; __device__ __forceinline__ int obid() { int b = (int)blockIdx.x; asm volatile("" : "+s"(b)); return b; }
; __device__ __forceinline__ float bflo(unsigned u) { return __uint_as_float(u << 16); }
; __device__ __forceinline__ float bfhi(unsigned u) { return __uint_as_float(u & 0xffff0000u); }
; __device__ __forceinline__ void ph_alt(const Params& p_) {
;     ...
;     for (int r = obid() * 8 + wave; r < NB * DG; r += gridDim.x * 8) {
;         const u32x4* src = (const u32x4*)(PQF + (size_t)r * 4096) + lane; float acc = 0.f;
; #pragma unroll
;         for (int j = 0; j < 4; ++j) { const u32x4 v = src[64 * j];
;             acc += (bflo(v.x) - bfhi(v.x)) + (bflo(v.y) - bfhi(v.y)) + (bflo(v.z) - bfhi(v.z)) + (bflo(v.w) - bfhi(v.w)); }
;         acc = wave_sum(acc);
;         if (lane == 0) dst[r] = acc;
;     }
.LBB0_600:
	v_ashrrev_i32_e32 v3, 31, v2
	s_waitcnt lgkmcnt(0)
	v_lshlrev_b64 v[12:13], 13, v[2:3]
	v_lshl_add_u64 v[16:17], v[4:5], 0, v[12:13]
	global_load_dwordx4 v[12:15], v[16:17], off
	global_load_dwordx4 v[20:23], v[16:17], off offset:1024
	global_load_dwordx4 v[24:27], v[16:17], off offset:2048
	global_load_dwordx4 v[28:31], v[16:17], off offset:3072
	s_waitcnt vmcnt(0)
	v_lshlrev_b32_e32 v11, 16, v12
	v_and_b32_e32 v12, 0xffff0000, v12
	v_sub_f32_e32 v11, v11, v12
	v_lshlrev_b32_e32 v12, 16, v13
	v_and_b32_e32 v13, 0xffff0000, v13
	v_sub_f32_e32 v12, v12, v13
	v_add_f32_e32 v11, v11, v12
	v_lshlrev_b32_e32 v12, 16, v14
	v_and_b32_e32 v13, 0xffff0000, v14
	v_sub_f32_e32 v12, v12, v13
	v_add_f32_e32 v11, v12, v11
	v_lshlrev_b32_e32 v12, 16, v15
	v_and_b32_e32 v13, 0xffff0000, v15
	v_sub_f32_e32 v12, v12, v13
	v_add_f32_e32 v11, v12, v11
	v_mov_b64_e32 v[12:13], v[20:21]
	v_mov_b64_e32 v[14:15], v[22:23]
	v_add_f32_e32 v11, 0, v11
	s_waitcnt vmcnt(0)
	v_lshlrev_b32_e32 v18, 16, v12
	v_and_b32_e32 v12, 0xffff0000, v12
	v_sub_f32_e32 v12, v18, v12
	v_lshlrev_b32_e32 v18, 16, v13
	v_and_b32_e32 v13, 0xffff0000, v13
	v_sub_f32_e32 v13, v18, v13
	v_add_f32_e32 v12, v12, v13
	v_lshlrev_b32_e32 v13, 16, v14
	v_and_b32_e32 v14, 0xffff0000, v14
	v_sub_f32_e32 v13, v13, v14
	v_add_f32_e32 v12, v13, v12
	v_lshlrev_b32_e32 v13, 16, v15
	v_and_b32_e32 v14, 0xffff0000, v15
	v_sub_f32_e32 v13, v13, v14
	v_add_f32_e32 v12, v13, v12
	v_add_f32_e32 v11, v11, v12
	v_mov_b64_e32 v[12:13], v[24:25]
	v_mov_b64_e32 v[14:15], v[26:27]
	s_waitcnt vmcnt(0)
	v_lshlrev_b32_e32 v18, 16, v12
	v_and_b32_e32 v12, 0xffff0000, v12
	v_sub_f32_e32 v12, v18, v12
	v_lshlrev_b32_e32 v18, 16, v13
	v_and_b32_e32 v13, 0xffff0000, v13
	v_sub_f32_e32 v13, v18, v13
	v_add_f32_e32 v12, v12, v13
	v_lshlrev_b32_e32 v13, 16, v14
	v_and_b32_e32 v14, 0xffff0000, v14
	v_sub_f32_e32 v13, v13, v14
	v_add_f32_e32 v12, v13, v12
	v_lshlrev_b32_e32 v13, 16, v15
	v_and_b32_e32 v14, 0xffff0000, v15
	v_sub_f32_e32 v13, v13, v14
	v_add_f32_e32 v12, v13, v12
	v_add_f32_e32 v11, v11, v12
	v_mov_b64_e32 v[12:13], v[28:29]
	v_mov_b64_e32 v[14:15], v[30:31]
	s_waitcnt vmcnt(0)
	v_lshlrev_b32_e32 v16, 16, v12
	v_and_b32_e32 v12, 0xffff0000, v12
	v_sub_f32_e32 v12, v16, v12
	v_lshlrev_b32_e32 v16, 16, v13
	v_and_b32_e32 v13, 0xffff0000, v13
	v_sub_f32_e32 v13, v16, v13
	v_add_f32_e32 v12, v12, v13
	v_lshlrev_b32_e32 v13, 16, v14
	v_and_b32_e32 v14, 0xffff0000, v14
	v_sub_f32_e32 v13, v13, v14
	v_add_f32_e32 v12, v13, v12
	v_lshlrev_b32_e32 v13, 16, v15
	v_and_b32_e32 v14, 0xffff0000, v15
	v_sub_f32_e32 v13, v13, v14
	v_add_f32_e32 v12, v13, v12
	v_add_f32_e32 v11, v11, v12
	s_nop 1
	v_mov_b32_dpp v12, v11 quad_perm:[1,0,3,2] row_mask:0xf bank_mask:0xf
	s_waitcnt lgkmcnt(0)
	v_add_f32_e32 v11, v11, v12
	s_nop 1
	v_mov_b32_dpp v12, v11 quad_perm:[2,3,0,1] row_mask:0xf bank_mask:0xf
	s_waitcnt lgkmcnt(0)
	v_add_f32_e32 v11, v11, v12
	s_nop 1
	v_mov_b32_dpp v12, v11 row_half_mirror row_mask:0xf bank_mask:0xf
	s_waitcnt lgkmcnt(0)
	v_add_f32_e32 v11, v11, v12
	s_nop 1
	v_mov_b32_dpp v12, v11 row_mirror row_mask:0xf bank_mask:0xf
	s_waitcnt lgkmcnt(0)
	v_add_f32_e32 v11, v11, v12
	ds_bpermute_b32 v12, v9, v11
	s_waitcnt lgkmcnt(0)
	v_add_f32_e32 v11, v11, v12
	ds_bpermute_b32 v12, v10, v11
	s_and_saveexec_b64 s[36:37], vcc
	s_cbranch_execz .LBB0_599
	s_waitcnt lgkmcnt(0)
	v_add_f32_e32 v11, v11, v12
	v_lshl_add_u64 v[12:13], v[2:3], 2, s[40:41]
	global_store_dword v[12:13], v11, off
	s_branch .LBB0_599
